# v022 plus: the post-K-loop s_waitcnt vmcnt(0) that guards the (long-landed) row scales relaxed to a counted vmcnt(6) in the P1 and both P3 GEMMs, so the epilogue no longer waits for the next tile's pr
# speedup vs baseline: 1.0022x; 1.0011x over previous
.LBB0_127:
	ds_read_b128 v[176:179], v167
	ds_read_b128 v[180:183], v167 offset:1024
	ds_read_b128 v[186:189], v167 offset:2048
	ds_read_b128 v[190:193], v167 offset:3072
	s_add_u32 s40, s38, 0xfff00080
	s_addc_u32 s41, s39, -1
	s_cmp_eq_u32 s54, 60
	s_cselect_b32 s43, s6, s41
	s_cselect_b32 s42, s7, s40
	s_cselect_b32 s41, s9, s29
	s_cselect_b32 s40, s11, s27
	v_lshl_add_u64 v[156:157], s[38:39], 0, v[138:139]
	s_add_i32 m0, s44, 0xc000
	ds_read_b128 v[194:197], v168
	ds_read_b128 v[198:201], v168 offset:1024
	ds_read_b128 v[202:205], v168 offset:2048
	ds_read_b128 v[206:209], v168 offset:3072
	ds_read_b128 v[210:213], v168 offset:4096
	ds_read_b128 v[214:217], v168 offset:5120
	ds_read_b128 v[218:221], v168 offset:6144
	ds_read_b128 v[222:225], v168 offset:7168
	global_load_lds_dwordx4 v[156:157], off
	v_lshl_add_u64 v[156:157], s[38:39], 0, v[140:141]
	s_add_i32 m0, s44, 0xe000
	s_nop 0
	global_load_lds_dwordx4 v[156:157], off
	s_waitcnt lgkmcnt(8)
	s_barrier
	s_waitcnt lgkmcnt(0)
	s_waitcnt lgkmcnt(0)
	v_mfma_f32_16x16x32_bf16 v[124:127], v[176:179], v[194:197], v[124:127]
	v_mfma_f32_16x16x32_bf16 v[124:127], v[180:183], v[198:201], v[124:127]
	v_mfma_f32_16x16x32_bf16 v[120:123], v[186:189], v[194:197], v[120:123]
	v_mfma_f32_16x16x32_bf16 v[120:123], v[190:193], v[198:201], v[120:123]
	v_mfma_f32_16x16x32_bf16 v[108:111], v[176:179], v[202:205], v[108:111]
	v_mfma_f32_16x16x32_bf16 v[108:111], v[180:183], v[206:209], v[108:111]
	v_mfma_f32_16x16x32_bf16 v[104:107], v[186:189], v[202:205], v[104:107]
	v_mfma_f32_16x16x32_bf16 v[104:107], v[190:193], v[206:209], v[104:107]
	v_mfma_f32_16x16x32_bf16 v[92:95], v[176:179], v[210:213], v[92:95]
	v_mfma_f32_16x16x32_bf16 v[92:95], v[180:183], v[214:217], v[92:95]
	v_mfma_f32_16x16x32_bf16 v[88:91], v[186:189], v[210:213], v[88:91]
	v_mfma_f32_16x16x32_bf16 v[88:91], v[190:193], v[214:217], v[88:91]
	v_mfma_f32_16x16x32_bf16 v[76:79], v[176:179], v[218:221], v[76:79]
	v_mfma_f32_16x16x32_bf16 v[76:79], v[180:183], v[222:225], v[76:79]
	v_mfma_f32_16x16x32_bf16 v[72:75], v[186:189], v[218:221], v[72:75]
	v_mfma_f32_16x16x32_bf16 v[72:75], v[190:193], v[222:225], v[72:75]
	s_barrier
	s_add_i32 s55, s72, s5
	v_lshl_add_u64 v[156:157], s[40:41], 0, v[130:131]
	s_mov_b32 m0, s55
	ds_read_b128 v[226:229], v169
	ds_read_b128 v[230:233], v169 offset:1024
	ds_read_b128 v[234:237], v169 offset:2048
	ds_read_b128 v[238:241], v169 offset:3072
	global_load_lds_dwordx4 v[156:157], off
	v_lshl_add_u64 v[162:163], s[40:41], 0, v[134:135]
	s_add_i32 m0, s55, 0x2000
	s_nop 0
	global_load_lds_dwordx4 v[162:163], off
	s_barrier
	s_waitcnt lgkmcnt(0)
	s_waitcnt lgkmcnt(0)
	v_mfma_f32_16x16x32_bf16 v[116:119], v[226:229], v[194:197], v[116:119]
	v_mfma_f32_16x16x32_bf16 v[116:119], v[230:233], v[198:201], v[116:119]
	v_mfma_f32_16x16x32_bf16 v[112:115], v[234:237], v[194:197], v[112:115]
	v_mfma_f32_16x16x32_bf16 v[112:115], v[238:241], v[198:201], v[112:115]
	v_mfma_f32_16x16x32_bf16 v[100:103], v[226:229], v[202:205], v[100:103]
	v_mfma_f32_16x16x32_bf16 v[100:103], v[230:233], v[206:209], v[100:103]
	v_mfma_f32_16x16x32_bf16 v[96:99], v[234:237], v[202:205], v[96:99]
	v_mfma_f32_16x16x32_bf16 v[96:99], v[238:241], v[206:209], v[96:99]
	v_mfma_f32_16x16x32_bf16 v[84:87], v[226:229], v[210:213], v[84:87]
	v_mfma_f32_16x16x32_bf16 v[84:87], v[230:233], v[214:217], v[84:87]
	v_mfma_f32_16x16x32_bf16 v[80:83], v[234:237], v[210:213], v[80:83]
	v_mfma_f32_16x16x32_bf16 v[80:83], v[238:241], v[214:217], v[80:83]
	v_mfma_f32_16x16x32_bf16 v[68:71], v[226:229], v[218:221], v[68:71]
	v_mfma_f32_16x16x32_bf16 v[68:71], v[230:233], v[222:225], v[68:71]
	v_mfma_f32_16x16x32_bf16 v[64:67], v[234:237], v[218:221], v[64:67]
	v_mfma_f32_16x16x32_bf16 v[64:67], v[238:241], v[222:225], v[64:67]
	s_mov_b32 m0, s44
	v_lshl_add_u64 v[170:171], s[42:43], 0, v[128:129]
	s_barrier
	ds_read_b128 v[194:197], v168 offset:16384
	ds_read_b128 v[198:201], v168 offset:17408
	ds_read_b128 v[202:205], v168 offset:18432
	ds_read_b128 v[206:209], v168 offset:19456
	ds_read_b128 v[210:213], v168 offset:20480
	ds_read_b128 v[214:217], v168 offset:21504
	ds_read_b128 v[218:221], v168 offset:22528
	ds_read_b128 v[222:225], v168 offset:23552
	global_load_lds_dwordx4 v[170:171], off
	v_lshl_add_u64 v[242:243], s[42:43], 0, v[132:133]
	s_mov_b32 m0, s45
	s_nop 0
	global_load_lds_dwordx4 v[242:243], off
	s_barrier
	s_waitcnt lgkmcnt(0)
	s_waitcnt lgkmcnt(0)
	v_mfma_f32_16x16x32_bf16 v[60:63], v[176:179], v[194:197], v[60:63]
	v_mfma_f32_16x16x32_bf16 v[60:63], v[180:183], v[198:201], v[60:63]
	v_mfma_f32_16x16x32_bf16 v[56:59], v[186:189], v[194:197], v[56:59]
	v_mfma_f32_16x16x32_bf16 v[56:59], v[190:193], v[198:201], v[56:59]
	v_mfma_f32_16x16x32_bf16 v[44:47], v[176:179], v[202:205], v[44:47]
	v_mfma_f32_16x16x32_bf16 v[44:47], v[180:183], v[206:209], v[44:47]
	v_mfma_f32_16x16x32_bf16 v[40:43], v[186:189], v[202:205], v[40:43]
	v_mfma_f32_16x16x32_bf16 v[40:43], v[190:193], v[206:209], v[40:43]
	v_mfma_f32_16x16x32_bf16 v[28:31], v[176:179], v[210:213], v[28:31]
	v_mfma_f32_16x16x32_bf16 v[28:31], v[180:183], v[214:217], v[28:31]
	v_mfma_f32_16x16x32_bf16 v[24:27], v[186:189], v[210:213], v[24:27]
	v_mfma_f32_16x16x32_bf16 v[24:27], v[190:193], v[214:217], v[24:27]
	v_mfma_f32_16x16x32_bf16 v[12:15], v[176:179], v[218:221], v[12:15]
	v_mfma_f32_16x16x32_bf16 v[12:15], v[180:183], v[222:225], v[12:15]
	v_mfma_f32_16x16x32_bf16 v[8:11], v[186:189], v[218:221], v[8:11]
	v_mfma_f32_16x16x32_bf16 v[8:11], v[190:193], v[222:225], v[8:11]
	s_barrier
	s_add_u32 s62, s40, 0x100000
	s_addc_u32 s63, s41, 0
	s_add_i32 s55, s73, s5
	v_lshl_add_u64 v[176:177], s[62:63], 0, v[130:131]
	s_mov_b32 m0, s55
	s_nop 0
	global_load_lds_dwordx4 v[176:177], off
	v_lshl_add_u64 v[176:177], s[62:63], 0, v[134:135]
	s_add_i32 m0, s55, 0x2000
	s_nop 0
	global_load_lds_dwordx4 v[176:177], off
	s_waitcnt vmcnt(6)
	s_barrier
	v_mfma_f32_16x16x32_bf16 v[52:55], v[226:229], v[194:197], v[52:55]
	v_mfma_f32_16x16x32_bf16 v[52:55], v[230:233], v[198:201], v[52:55]
	v_mfma_f32_16x16x32_bf16 v[48:51], v[234:237], v[194:197], v[48:51]
	v_mfma_f32_16x16x32_bf16 v[48:51], v[238:241], v[198:201], v[48:51]
	v_mfma_f32_16x16x32_bf16 v[36:39], v[226:229], v[202:205], v[36:39]
	v_mfma_f32_16x16x32_bf16 v[36:39], v[230:233], v[206:209], v[36:39]
	v_mfma_f32_16x16x32_bf16 v[32:35], v[234:237], v[202:205], v[32:35]
	v_mfma_f32_16x16x32_bf16 v[32:35], v[238:241], v[206:209], v[32:35]
	v_mfma_f32_16x16x32_bf16 v[20:23], v[226:229], v[210:213], v[20:23]
	v_mfma_f32_16x16x32_bf16 v[20:23], v[230:233], v[214:217], v[20:23]
	v_mfma_f32_16x16x32_bf16 v[16:19], v[234:237], v[210:213], v[16:19]
	v_mfma_f32_16x16x32_bf16 v[16:19], v[238:241], v[214:217], v[16:19]
	v_mfma_f32_16x16x32_bf16 v[4:7], v[226:229], v[218:221], v[4:7]
	v_mfma_f32_16x16x32_bf16 v[4:7], v[230:233], v[222:225], v[4:7]
	v_mfma_f32_16x16x32_bf16 v[0:3], v[234:237], v[218:221], v[0:3]
	v_mfma_f32_16x16x32_bf16 v[0:3], v[238:241], v[222:225], v[0:3]
	s_add_i32 s55, 0, 0x18000
	v_add_u32_e32 v137, s55, v165
	s_barrier
	ds_read_b128 v[176:179], v137
	ds_read_b128 v[180:183], v137 offset:1024
	ds_read_b128 v[186:189], v137 offset:2048
	ds_read_b128 v[190:193], v137 offset:3072
	s_add_u32 s42, s42, 0x100000
	s_addc_u32 s43, s43, 0
	s_mov_b32 m0, s46
	v_lshl_add_u64 v[226:227], s[42:43], 0, v[128:129]
	ds_read_b128 v[194:197], v168 offset:32768
	ds_read_b128 v[198:201], v168 offset:33792
	ds_read_b128 v[202:205], v168 offset:34816
	ds_read_b128 v[206:209], v168 offset:35840
	ds_read_b128 v[210:213], v168 offset:36864
	ds_read_b128 v[214:217], v168 offset:37888
	ds_read_b128 v[218:221], v168 offset:38912
	ds_read_b128 v[222:225], v168 offset:39936
	global_load_lds_dwordx4 v[226:227], off
	v_lshl_add_u64 v[226:227], s[42:43], 0, v[132:133]
	s_mov_b32 m0, s47
	s_nop 0
	global_load_lds_dwordx4 v[226:227], off
	s_waitcnt lgkmcnt(8)
	s_barrier
	s_waitcnt lgkmcnt(0)
	s_waitcnt lgkmcnt(0)
	v_mfma_f32_16x16x32_bf16 v[124:127], v[176:179], v[194:197], v[124:127]
	v_mfma_f32_16x16x32_bf16 v[124:127], v[180:183], v[198:201], v[124:127]
	v_mfma_f32_16x16x32_bf16 v[120:123], v[186:189], v[194:197], v[120:123]
	v_mfma_f32_16x16x32_bf16 v[120:123], v[190:193], v[198:201], v[120:123]
	v_mfma_f32_16x16x32_bf16 v[108:111], v[176:179], v[202:205], v[108:111]
	v_mfma_f32_16x16x32_bf16 v[108:111], v[180:183], v[206:209], v[108:111]
	v_mfma_f32_16x16x32_bf16 v[104:107], v[186:189], v[202:205], v[104:107]
	v_mfma_f32_16x16x32_bf16 v[104:107], v[190:193], v[206:209], v[104:107]
	v_mfma_f32_16x16x32_bf16 v[92:95], v[176:179], v[210:213], v[92:95]
	v_mfma_f32_16x16x32_bf16 v[92:95], v[180:183], v[214:217], v[92:95]
	v_mfma_f32_16x16x32_bf16 v[88:91], v[186:189], v[210:213], v[88:91]
	v_mfma_f32_16x16x32_bf16 v[88:91], v[190:193], v[214:217], v[88:91]
	v_mfma_f32_16x16x32_bf16 v[76:79], v[176:179], v[218:221], v[76:79]
	v_mfma_f32_16x16x32_bf16 v[76:79], v[180:183], v[222:225], v[76:79]
	v_mfma_f32_16x16x32_bf16 v[72:75], v[186:189], v[218:221], v[72:75]
	v_mfma_f32_16x16x32_bf16 v[72:75], v[190:193], v[222:225], v[72:75]
	s_barrier
	s_add_i32 s42, 0, 0x1c000
	s_add_i32 s43, s55, s5
	v_add_u32_e32 v137, s42, v165
	v_lshl_add_u64 v[156:157], v[156:157], 0, s[24:25]
	s_mov_b32 m0, s43
	ds_read_b128 v[226:229], v137
	ds_read_b128 v[230:233], v137 offset:1024
	ds_read_b128 v[234:237], v137 offset:2048
	ds_read_b128 v[238:241], v137 offset:3072
	global_load_lds_dwordx4 v[156:157], off
	v_lshl_add_u64 v[156:157], v[162:163], 0, s[24:25]
	s_add_i32 m0, s43, 0x2000
	s_nop 0
	global_load_lds_dwordx4 v[156:157], off
	s_barrier
	s_waitcnt lgkmcnt(0)
	s_waitcnt lgkmcnt(0)
	v_mfma_f32_16x16x32_bf16 v[116:119], v[226:229], v[194:197], v[116:119]
	v_mfma_f32_16x16x32_bf16 v[116:119], v[230:233], v[198:201], v[116:119]
	v_mfma_f32_16x16x32_bf16 v[112:115], v[234:237], v[194:197], v[112:115]
	v_mfma_f32_16x16x32_bf16 v[112:115], v[238:241], v[198:201], v[112:115]
	v_mfma_f32_16x16x32_bf16 v[100:103], v[226:229], v[202:205], v[100:103]
	v_mfma_f32_16x16x32_bf16 v[100:103], v[230:233], v[206:209], v[100:103]
	v_mfma_f32_16x16x32_bf16 v[96:99], v[234:237], v[202:205], v[96:99]
	v_mfma_f32_16x16x32_bf16 v[96:99], v[238:241], v[206:209], v[96:99]
	v_mfma_f32_16x16x32_bf16 v[84:87], v[226:229], v[210:213], v[84:87]
	v_mfma_f32_16x16x32_bf16 v[84:87], v[230:233], v[214:217], v[84:87]
	v_mfma_f32_16x16x32_bf16 v[80:83], v[234:237], v[210:213], v[80:83]
	v_mfma_f32_16x16x32_bf16 v[80:83], v[238:241], v[214:217], v[80:83]
	v_mfma_f32_16x16x32_bf16 v[68:71], v[226:229], v[218:221], v[68:71]
	v_mfma_f32_16x16x32_bf16 v[68:71], v[230:233], v[222:225], v[68:71]
	v_mfma_f32_16x16x32_bf16 v[64:67], v[234:237], v[218:221], v[64:67]
	v_mfma_f32_16x16x32_bf16 v[64:67], v[238:241], v[222:225], v[64:67]
	s_mov_b32 m0, s49
	v_lshl_add_u64 v[156:157], v[170:171], 0, s[24:25]
	s_barrier
	ds_read_b128 v[194:197], v168 offset:49152
	ds_read_b128 v[198:201], v168 offset:50176
	ds_read_b128 v[202:205], v168 offset:51200
	ds_read_b128 v[206:209], v168 offset:52224
	ds_read_b128 v[210:213], v168 offset:53248
	ds_read_b128 v[214:217], v168 offset:54272
	ds_read_b128 v[218:221], v168 offset:55296
	ds_read_b128 v[222:225], v168 offset:56320
	global_load_lds_dwordx4 v[156:157], off
	v_lshl_add_u64 v[156:157], v[242:243], 0, s[24:25]
	s_mov_b32 m0, s50
	s_nop 0
	global_load_lds_dwordx4 v[156:157], off
	s_barrier
	s_waitcnt lgkmcnt(0)
	s_waitcnt lgkmcnt(0)
	v_mfma_f32_16x16x32_bf16 v[60:63], v[176:179], v[194:197], v[60:63]
	v_mfma_f32_16x16x32_bf16 v[60:63], v[180:183], v[198:201], v[60:63]
	v_mfma_f32_16x16x32_bf16 v[56:59], v[186:189], v[194:197], v[56:59]
	v_mfma_f32_16x16x32_bf16 v[56:59], v[190:193], v[198:201], v[56:59]
	v_mfma_f32_16x16x32_bf16 v[44:47], v[176:179], v[202:205], v[44:47]
	v_mfma_f32_16x16x32_bf16 v[44:47], v[180:183], v[206:209], v[44:47]
	v_mfma_f32_16x16x32_bf16 v[40:43], v[186:189], v[202:205], v[40:43]
	v_mfma_f32_16x16x32_bf16 v[40:43], v[190:193], v[206:209], v[40:43]
	v_mfma_f32_16x16x32_bf16 v[28:31], v[176:179], v[210:213], v[28:31]
	v_mfma_f32_16x16x32_bf16 v[28:31], v[180:183], v[214:217], v[28:31]
	v_mfma_f32_16x16x32_bf16 v[24:27], v[186:189], v[210:213], v[24:27]
	v_mfma_f32_16x16x32_bf16 v[24:27], v[190:193], v[214:217], v[24:27]
	v_mfma_f32_16x16x32_bf16 v[12:15], v[176:179], v[218:221], v[12:15]
	v_mfma_f32_16x16x32_bf16 v[12:15], v[180:183], v[222:225], v[12:15]
	v_mfma_f32_16x16x32_bf16 v[8:11], v[186:189], v[218:221], v[8:11]
	v_mfma_f32_16x16x32_bf16 v[8:11], v[190:193], v[222:225], v[8:11]
	s_barrier
	s_add_u32 s40, s40, 0x100080
	s_addc_u32 s41, s41, 0
	s_add_i32 s42, s42, s5
	v_lshl_add_u64 v[156:157], s[40:41], 0, v[130:131]
	s_mov_b32 m0, s42
	s_nop 0
	global_load_lds_dwordx4 v[156:157], off
	v_lshl_add_u64 v[156:157], s[40:41], 0, v[134:135]
	s_add_i32 m0, s42, 0x2000
	s_nop 0
	global_load_lds_dwordx4 v[156:157], off
	s_waitcnt vmcnt(6)
	s_barrier
	v_mfma_f32_16x16x32_bf16 v[52:55], v[226:229], v[194:197], v[52:55]
	v_mfma_f32_16x16x32_bf16 v[52:55], v[230:233], v[198:201], v[52:55]
	v_mfma_f32_16x16x32_bf16 v[48:51], v[234:237], v[194:197], v[48:51]
	v_mfma_f32_16x16x32_bf16 v[48:51], v[238:241], v[198:201], v[48:51]
	v_mfma_f32_16x16x32_bf16 v[36:39], v[226:229], v[202:205], v[36:39]
	v_mfma_f32_16x16x32_bf16 v[36:39], v[230:233], v[206:209], v[36:39]
	v_mfma_f32_16x16x32_bf16 v[32:35], v[234:237], v[202:205], v[32:35]
	v_mfma_f32_16x16x32_bf16 v[32:35], v[238:241], v[206:209], v[32:35]
	v_mfma_f32_16x16x32_bf16 v[20:23], v[226:229], v[210:213], v[20:23]
	v_mfma_f32_16x16x32_bf16 v[20:23], v[230:233], v[214:217], v[20:23]
	v_mfma_f32_16x16x32_bf16 v[16:19], v[234:237], v[210:213], v[16:19]
	v_mfma_f32_16x16x32_bf16 v[16:19], v[238:241], v[214:217], v[16:19]
	v_mfma_f32_16x16x32_bf16 v[4:7], v[226:229], v[218:221], v[4:7]
	v_mfma_f32_16x16x32_bf16 v[4:7], v[230:233], v[222:225], v[4:7]
	v_mfma_f32_16x16x32_bf16 v[0:3], v[234:237], v[218:221], v[0:3]
	v_mfma_f32_16x16x32_bf16 v[0:3], v[238:241], v[222:225], v[0:3]
	s_add_i32 s54, s54, 2
	s_add_u32 s38, s38, 0x100
	s_addc_u32 s39, s39, 0
	s_add_u32 s27, s27, 0x100
	s_addc_u32 s29, s29, 0
	s_cmp_gt_u32 s54, 61
	s_barrier
	s_cbranch_scc0 .LBB0_127
	v_lshl_or_b32 v156, s8, 8, v166
	s_waitcnt vmcnt(6)
	v_pk_mul_f32 v[126:127], v[160:161], v[126:127] op_sel_hi:[0,1]
	v_pk_mul_f32 v[124:125], v[160:161], v[124:125] op_sel_hi:[0,1]
	v_pk_mul_f32 v[122:123], v[160:161], v[122:123] op_sel_hi:[0,1]
	v_pk_mul_f32 v[162:163], v[160:161], v[120:121] op_sel_hi:[0,1]
	v_cmp_lt_i32_e64 s[8:9], s74, v156
	s_and_saveexec_b64 s[38:39], s[8:9]
	s_cbranch_execz .LBB0_130
	v_mul_f32_e32 v147, 0xbfb8aa3b, v126
	v_mul_f32_e32 v121, 0xbfb8aa3b, v162
	v_exp_f32_e32 v147, v147
	v_mul_f32_e32 v149, 0xbfb8aa3b, v122
	v_mul_f32_e32 v137, 0xbfb8aa3b, v125
	v_exp_f32_e32 v121, v121
	v_exp_f32_e32 v149, v149
	v_exp_f32_e32 v137, v137
	v_add_f32_e32 v147, 1.0, v147
	v_add_f32_e32 v121, 1.0, v121
	v_rcp_f32_e32 v176, v147
	v_add_f32_e32 v147, 1.0, v149
	v_mul_f32_e32 v149, 0xbfb8aa3b, v127
	v_mul_f32_e32 v120, 0xbfb8aa3b, v124
	v_rcp_f32_e32 v170, v121
	v_add_f32_e32 v121, 1.0, v137
	v_mul_f32_e32 v137, 0xbfb8aa3b, v163
	v_exp_f32_e32 v149, v149
	v_mul_f32_e32 v151, 0xbfb8aa3b, v123
	v_exp_f32_e32 v120, v120
	v_exp_f32_e32 v137, v137
	v_exp_f32_e32 v151, v151
	v_rcp_f32_e32 v178, v147
	v_add_f32_e32 v147, 1.0, v149
	v_add_f32_e32 v120, 1.0, v120
	v_add_f32_e32 v137, 1.0, v137
	v_rcp_f32_e32 v177, v147
	v_add_f32_e32 v147, 1.0, v151
	v_rcp_f32_e32 v120, v120
	v_rcp_f32_e32 v121, v121
	v_rcp_f32_e32 v179, v147
	v_rcp_f32_e32 v171, v137
	v_pk_mul_f32 v[126:127], v[126:127], v[176:177]
	v_pk_mul_f32 v[124:125], v[124:125], v[120:121]
	v_pk_mul_f32 v[122:123], v[122:123], v[178:179]
	v_pk_mul_f32 v[162:163], v[162:163], v[170:171]

.LBB0_301:
	ds_read_b128 v[160:163], v151
	ds_read_b128 v[164:167], v151 offset:1024
	ds_read_b128 v[168:171], v151 offset:2048
	ds_read_b128 v[176:179], v151 offset:3072
	s_add_u32 s44, s42, 0x100
	s_addc_u32 s45, s43, 0
	s_cmp_eq_u32 s83, 12
	s_cselect_b32 s49, s39, s45
	s_cselect_b32 s48, s38, s44
	s_cselect_b32 s47, s37, s82
	s_cselect_b32 s46, s62, s63
	v_lshl_add_u64 v[214:215], s[42:43], 0, v[142:143]
	s_add_i32 m0, s50, 0xc000
	ds_read_b128 v[180:183], v153
	ds_read_b128 v[186:189], v153 offset:1024
	ds_read_b128 v[190:193], v153 offset:2048
	ds_read_b128 v[194:197], v153 offset:3072
	ds_read_b128 v[198:201], v153 offset:4096
	ds_read_b128 v[202:205], v153 offset:5120
	ds_read_b128 v[206:209], v153 offset:6144
	ds_read_b128 v[210:213], v153 offset:7168
	global_load_lds_dwordx4 v[214:215], off
	v_lshl_add_u64 v[214:215], s[42:43], 0, v[144:145]
	s_add_i32 m0, s50, 0xe000
	s_nop 0
	global_load_lds_dwordx4 v[214:215], off
	s_waitcnt lgkmcnt(8)
	s_barrier
	s_waitcnt lgkmcnt(0)
	s_waitcnt lgkmcnt(0)
	v_mfma_f32_16x16x32_bf16 v[124:127], v[160:163], v[180:183], v[124:127]
	v_mfma_f32_16x16x32_bf16 v[124:127], v[164:167], v[186:189], v[124:127]
	v_mfma_f32_16x16x32_bf16 v[120:123], v[168:171], v[180:183], v[120:123]
	v_mfma_f32_16x16x32_bf16 v[120:123], v[176:179], v[186:189], v[120:123]
	v_mfma_f32_16x16x32_bf16 v[112:115], v[160:163], v[190:193], v[112:115]
	v_mfma_f32_16x16x32_bf16 v[112:115], v[164:167], v[194:197], v[112:115]
	v_mfma_f32_16x16x32_bf16 v[104:107], v[168:171], v[190:193], v[104:107]
	v_mfma_f32_16x16x32_bf16 v[104:107], v[176:179], v[194:197], v[104:107]
	v_mfma_f32_16x16x32_bf16 v[96:99], v[160:163], v[198:201], v[96:99]
	v_mfma_f32_16x16x32_bf16 v[96:99], v[164:167], v[202:205], v[96:99]
	v_mfma_f32_16x16x32_bf16 v[88:91], v[168:171], v[198:201], v[88:91]
	v_mfma_f32_16x16x32_bf16 v[88:91], v[176:179], v[202:205], v[88:91]
	v_mfma_f32_16x16x32_bf16 v[80:83], v[160:163], v[206:209], v[80:83]
	v_mfma_f32_16x16x32_bf16 v[80:83], v[164:167], v[210:213], v[80:83]
	v_mfma_f32_16x16x32_bf16 v[72:75], v[168:171], v[206:209], v[72:75]
	v_mfma_f32_16x16x32_bf16 v[72:75], v[176:179], v[210:213], v[72:75]
	s_barrier
	s_add_i32 s42, s76, s5
	v_lshl_add_u64 v[230:231], s[46:47], 0, v[132:133]
	s_mov_b32 m0, s42
	ds_read_b128 v[214:217], v155
	ds_read_b128 v[218:221], v155 offset:1024
	ds_read_b128 v[222:225], v155 offset:2048
	ds_read_b128 v[226:229], v155 offset:3072
	global_load_lds_dwordx4 v[230:231], off
	v_lshl_add_u64 v[232:233], s[46:47], 0, v[128:129]
	s_add_i32 m0, s42, 0x2000
	s_nop 0
	global_load_lds_dwordx4 v[232:233], off
	s_barrier
	s_waitcnt lgkmcnt(0)
	s_waitcnt lgkmcnt(0)
	v_mfma_f32_16x16x32_bf16 v[116:119], v[214:217], v[180:183], v[116:119]
	v_mfma_f32_16x16x32_bf16 v[116:119], v[218:221], v[186:189], v[116:119]
	v_mfma_f32_16x16x32_bf16 v[108:111], v[222:225], v[180:183], v[108:111]
	v_mfma_f32_16x16x32_bf16 v[108:111], v[226:229], v[186:189], v[108:111]
	v_mfma_f32_16x16x32_bf16 v[100:103], v[214:217], v[190:193], v[100:103]
	v_mfma_f32_16x16x32_bf16 v[100:103], v[218:221], v[194:197], v[100:103]
	v_mfma_f32_16x16x32_bf16 v[92:95], v[222:225], v[190:193], v[92:95]
	v_mfma_f32_16x16x32_bf16 v[92:95], v[226:229], v[194:197], v[92:95]
	v_mfma_f32_16x16x32_bf16 v[84:87], v[214:217], v[198:201], v[84:87]
	v_mfma_f32_16x16x32_bf16 v[84:87], v[218:221], v[202:205], v[84:87]
	v_mfma_f32_16x16x32_bf16 v[76:79], v[222:225], v[198:201], v[76:79]
	v_mfma_f32_16x16x32_bf16 v[76:79], v[226:229], v[202:205], v[76:79]
	v_mfma_f32_16x16x32_bf16 v[68:71], v[214:217], v[206:209], v[68:71]
	v_mfma_f32_16x16x32_bf16 v[68:71], v[218:221], v[210:213], v[68:71]
	v_mfma_f32_16x16x32_bf16 v[64:67], v[222:225], v[206:209], v[64:67]
	v_mfma_f32_16x16x32_bf16 v[64:67], v[226:229], v[210:213], v[64:67]
	s_mov_b32 m0, s50
	v_lshl_add_u64 v[234:235], s[48:49], 0, v[134:135]
	s_barrier
	ds_read_b128 v[180:183], v153 offset:16384
	ds_read_b128 v[186:189], v153 offset:17408
	ds_read_b128 v[190:193], v153 offset:18432
	ds_read_b128 v[194:197], v153 offset:19456
	ds_read_b128 v[198:201], v153 offset:20480
	ds_read_b128 v[202:205], v153 offset:21504
	ds_read_b128 v[206:209], v153 offset:22528
	ds_read_b128 v[210:213], v153 offset:23552
	global_load_lds_dwordx4 v[234:235], off
	v_lshl_add_u64 v[236:237], s[48:49], 0, v[130:131]
	s_mov_b32 m0, s51
	s_nop 0
	global_load_lds_dwordx4 v[236:237], off
	s_barrier
	s_waitcnt lgkmcnt(0)
	s_waitcnt lgkmcnt(0)
	v_mfma_f32_16x16x32_bf16 v[60:63], v[160:163], v[180:183], v[60:63]
	v_mfma_f32_16x16x32_bf16 v[60:63], v[164:167], v[186:189], v[60:63]
	v_mfma_f32_16x16x32_bf16 v[56:59], v[168:171], v[180:183], v[56:59]
	v_mfma_f32_16x16x32_bf16 v[56:59], v[176:179], v[186:189], v[56:59]
	v_mfma_f32_16x16x32_bf16 v[48:51], v[160:163], v[190:193], v[48:51]
	v_mfma_f32_16x16x32_bf16 v[48:51], v[164:167], v[194:197], v[48:51]
	v_mfma_f32_16x16x32_bf16 v[40:43], v[168:171], v[190:193], v[40:43]
	v_mfma_f32_16x16x32_bf16 v[40:43], v[176:179], v[194:197], v[40:43]
	v_mfma_f32_16x16x32_bf16 v[32:35], v[160:163], v[198:201], v[32:35]
	v_mfma_f32_16x16x32_bf16 v[32:35], v[164:167], v[202:205], v[32:35]
	v_mfma_f32_16x16x32_bf16 v[24:27], v[168:171], v[198:201], v[24:27]
	v_mfma_f32_16x16x32_bf16 v[24:27], v[176:179], v[202:205], v[24:27]
	v_mfma_f32_16x16x32_bf16 v[16:19], v[160:163], v[206:209], v[16:19]
	v_mfma_f32_16x16x32_bf16 v[16:19], v[164:167], v[210:213], v[16:19]
	v_mfma_f32_16x16x32_bf16 v[8:11], v[168:171], v[206:209], v[8:11]
	v_mfma_f32_16x16x32_bf16 v[8:11], v[176:179], v[210:213], v[8:11]
	s_barrier
	s_add_u32 s42, s46, 0x40000
	s_addc_u32 s43, s47, 0
	s_add_i32 s84, s77, s5
	v_lshl_add_u64 v[160:161], s[42:43], 0, v[132:133]
	s_mov_b32 m0, s84
	s_nop 0
	global_load_lds_dwordx4 v[160:161], off
	v_lshl_add_u64 v[160:161], s[42:43], 0, v[128:129]
	s_add_i32 m0, s84, 0x2000
	s_nop 0
	global_load_lds_dwordx4 v[160:161], off
	s_waitcnt vmcnt(6)
	s_barrier
	v_mfma_f32_16x16x32_bf16 v[52:55], v[214:217], v[180:183], v[52:55]
	v_mfma_f32_16x16x32_bf16 v[52:55], v[218:221], v[186:189], v[52:55]
	v_mfma_f32_16x16x32_bf16 v[44:47], v[222:225], v[180:183], v[44:47]
	v_mfma_f32_16x16x32_bf16 v[44:47], v[226:229], v[186:189], v[44:47]
	v_mfma_f32_16x16x32_bf16 v[36:39], v[214:217], v[190:193], v[36:39]
	v_mfma_f32_16x16x32_bf16 v[36:39], v[218:221], v[194:197], v[36:39]
	v_mfma_f32_16x16x32_bf16 v[28:31], v[222:225], v[190:193], v[28:31]
	v_mfma_f32_16x16x32_bf16 v[28:31], v[226:229], v[194:197], v[28:31]
	v_mfma_f32_16x16x32_bf16 v[20:23], v[214:217], v[198:201], v[20:23]
	v_mfma_f32_16x16x32_bf16 v[20:23], v[218:221], v[202:205], v[20:23]
	v_mfma_f32_16x16x32_bf16 v[12:15], v[222:225], v[198:201], v[12:15]
	v_mfma_f32_16x16x32_bf16 v[12:15], v[226:229], v[202:205], v[12:15]
	v_mfma_f32_16x16x32_bf16 v[4:7], v[214:217], v[206:209], v[4:7]
	v_mfma_f32_16x16x32_bf16 v[4:7], v[218:221], v[210:213], v[4:7]
	v_mfma_f32_16x16x32_bf16 v[0:3], v[222:225], v[206:209], v[0:3]
	v_mfma_f32_16x16x32_bf16 v[0:3], v[226:229], v[210:213], v[0:3]
	s_add_i32 s84, 0, 0x18000
	v_add_u32_e32 v157, s84, v139
	s_barrier
	ds_read_b128 v[160:163], v157
	ds_read_b128 v[164:167], v157 offset:1024
	ds_read_b128 v[168:171], v157 offset:2048
	ds_read_b128 v[176:179], v157 offset:3072
	s_add_u32 s42, s48, 0x170000
	s_addc_u32 s43, s49, 0
	s_mov_b32 m0, s52
	v_lshl_add_u64 v[214:215], s[42:43], 0, v[134:135]
	ds_read_b128 v[180:183], v153 offset:32768
	ds_read_b128 v[186:189], v153 offset:33792
	ds_read_b128 v[190:193], v153 offset:34816
	ds_read_b128 v[194:197], v153 offset:35840
	ds_read_b128 v[198:201], v153 offset:36864
	ds_read_b128 v[202:205], v153 offset:37888
	ds_read_b128 v[206:209], v153 offset:38912
	ds_read_b128 v[210:213], v153 offset:39936
	global_load_lds_dwordx4 v[214:215], off
	v_lshl_add_u64 v[214:215], s[42:43], 0, v[130:131]
	s_mov_b32 m0, s53
	s_nop 0
	global_load_lds_dwordx4 v[214:215], off
	s_waitcnt lgkmcnt(8)
	s_barrier
	s_waitcnt lgkmcnt(0)
	s_waitcnt lgkmcnt(0)
	v_mfma_f32_16x16x32_bf16 v[124:127], v[160:163], v[180:183], v[124:127]
	v_mfma_f32_16x16x32_bf16 v[124:127], v[164:167], v[186:189], v[124:127]
	v_mfma_f32_16x16x32_bf16 v[120:123], v[168:171], v[180:183], v[120:123]
	v_mfma_f32_16x16x32_bf16 v[120:123], v[176:179], v[186:189], v[120:123]
	v_mfma_f32_16x16x32_bf16 v[112:115], v[160:163], v[190:193], v[112:115]
	v_mfma_f32_16x16x32_bf16 v[112:115], v[164:167], v[194:197], v[112:115]
	v_mfma_f32_16x16x32_bf16 v[104:107], v[168:171], v[190:193], v[104:107]
	v_mfma_f32_16x16x32_bf16 v[104:107], v[176:179], v[194:197], v[104:107]
	v_mfma_f32_16x16x32_bf16 v[96:99], v[160:163], v[198:201], v[96:99]
	v_mfma_f32_16x16x32_bf16 v[96:99], v[164:167], v[202:205], v[96:99]
	v_mfma_f32_16x16x32_bf16 v[88:91], v[168:171], v[198:201], v[88:91]
	v_mfma_f32_16x16x32_bf16 v[88:91], v[176:179], v[202:205], v[88:91]
	v_mfma_f32_16x16x32_bf16 v[80:83], v[160:163], v[206:209], v[80:83]
	v_mfma_f32_16x16x32_bf16 v[80:83], v[164:167], v[210:213], v[80:83]
	v_mfma_f32_16x16x32_bf16 v[72:75], v[168:171], v[206:209], v[72:75]
	v_mfma_f32_16x16x32_bf16 v[72:75], v[176:179], v[210:213], v[72:75]
	s_barrier
	s_add_i32 s48, 0, 0x1c000
	s_add_i32 s42, s84, s5
	v_add_u32_e32 v157, s48, v139
	v_lshl_add_u64 v[230:231], v[230:231], 0, s[10:11]
	s_mov_b32 m0, s42
	ds_read_b128 v[214:217], v157
	ds_read_b128 v[218:221], v157 offset:1024
	ds_read_b128 v[222:225], v157 offset:2048
	ds_read_b128 v[226:229], v157 offset:3072
	global_load_lds_dwordx4 v[230:231], off
	v_lshl_add_u64 v[230:231], v[232:233], 0, s[10:11]
	s_add_i32 m0, s42, 0x2000
	s_nop 0
	global_load_lds_dwordx4 v[230:231], off
	s_barrier
	s_waitcnt lgkmcnt(0)
	s_waitcnt lgkmcnt(0)
	v_mfma_f32_16x16x32_bf16 v[116:119], v[214:217], v[180:183], v[116:119]
	v_mfma_f32_16x16x32_bf16 v[116:119], v[218:221], v[186:189], v[116:119]
	v_mfma_f32_16x16x32_bf16 v[108:111], v[222:225], v[180:183], v[108:111]
	v_mfma_f32_16x16x32_bf16 v[108:111], v[226:229], v[186:189], v[108:111]
	v_mfma_f32_16x16x32_bf16 v[100:103], v[214:217], v[190:193], v[100:103]
	v_mfma_f32_16x16x32_bf16 v[100:103], v[218:221], v[194:197], v[100:103]
	v_mfma_f32_16x16x32_bf16 v[92:95], v[222:225], v[190:193], v[92:95]
	v_mfma_f32_16x16x32_bf16 v[92:95], v[226:229], v[194:197], v[92:95]
	v_mfma_f32_16x16x32_bf16 v[84:87], v[214:217], v[198:201], v[84:87]
	v_mfma_f32_16x16x32_bf16 v[84:87], v[218:221], v[202:205], v[84:87]
	v_mfma_f32_16x16x32_bf16 v[76:79], v[222:225], v[198:201], v[76:79]
	v_mfma_f32_16x16x32_bf16 v[76:79], v[226:229], v[202:205], v[76:79]
	v_mfma_f32_16x16x32_bf16 v[68:71], v[214:217], v[206:209], v[68:71]
	v_mfma_f32_16x16x32_bf16 v[68:71], v[218:221], v[210:213], v[68:71]
	v_mfma_f32_16x16x32_bf16 v[64:67], v[222:225], v[206:209], v[64:67]
	v_mfma_f32_16x16x32_bf16 v[64:67], v[226:229], v[210:213], v[64:67]
	s_mov_b32 m0, s55
	v_lshl_add_u64 v[230:231], v[234:235], 0, s[10:11]
	s_barrier
	ds_read_b128 v[180:183], v153 offset:49152
	ds_read_b128 v[186:189], v153 offset:50176
	ds_read_b128 v[190:193], v153 offset:51200
	ds_read_b128 v[194:197], v153 offset:52224
	ds_read_b128 v[198:201], v153 offset:53248
	ds_read_b128 v[202:205], v153 offset:54272
	ds_read_b128 v[206:209], v153 offset:55296
	ds_read_b128 v[210:213], v153 offset:56320
	global_load_lds_dwordx4 v[230:231], off
	v_lshl_add_u64 v[230:231], v[236:237], 0, s[10:11]
	s_mov_b32 m0, s61
	s_nop 0
	global_load_lds_dwordx4 v[230:231], off
	s_barrier
	s_waitcnt lgkmcnt(0)
	s_waitcnt lgkmcnt(0)
	v_mfma_f32_16x16x32_bf16 v[60:63], v[160:163], v[180:183], v[60:63]
	v_mfma_f32_16x16x32_bf16 v[60:63], v[164:167], v[186:189], v[60:63]
	v_mfma_f32_16x16x32_bf16 v[56:59], v[168:171], v[180:183], v[56:59]
	v_mfma_f32_16x16x32_bf16 v[56:59], v[176:179], v[186:189], v[56:59]
	v_mfma_f32_16x16x32_bf16 v[48:51], v[160:163], v[190:193], v[48:51]
	v_mfma_f32_16x16x32_bf16 v[48:51], v[164:167], v[194:197], v[48:51]
	v_mfma_f32_16x16x32_bf16 v[40:43], v[168:171], v[190:193], v[40:43]
	v_mfma_f32_16x16x32_bf16 v[40:43], v[176:179], v[194:197], v[40:43]
	v_mfma_f32_16x16x32_bf16 v[32:35], v[160:163], v[198:201], v[32:35]
	v_mfma_f32_16x16x32_bf16 v[32:35], v[164:167], v[202:205], v[32:35]
	v_mfma_f32_16x16x32_bf16 v[24:27], v[168:171], v[198:201], v[24:27]
	v_mfma_f32_16x16x32_bf16 v[24:27], v[176:179], v[202:205], v[24:27]
	v_mfma_f32_16x16x32_bf16 v[16:19], v[160:163], v[206:209], v[16:19]
	v_mfma_f32_16x16x32_bf16 v[16:19], v[164:167], v[210:213], v[16:19]
	v_mfma_f32_16x16x32_bf16 v[8:11], v[168:171], v[206:209], v[8:11]
	v_mfma_f32_16x16x32_bf16 v[8:11], v[176:179], v[210:213], v[8:11]
	s_barrier
	s_add_u32 s42, s46, 0x40080
	s_addc_u32 s43, s47, 0
	s_add_i32 s46, s48, s5
	v_lshl_add_u64 v[160:161], s[42:43], 0, v[132:133]
	s_mov_b32 m0, s46
	s_nop 0
	global_load_lds_dwordx4 v[160:161], off
	v_lshl_add_u64 v[160:161], s[42:43], 0, v[128:129]
	s_add_i32 m0, s46, 0x2000
	s_nop 0
	global_load_lds_dwordx4 v[160:161], off
	s_waitcnt vmcnt(6)
	s_barrier
	v_mfma_f32_16x16x32_bf16 v[52:55], v[214:217], v[180:183], v[52:55]
	v_mfma_f32_16x16x32_bf16 v[52:55], v[218:221], v[186:189], v[52:55]
	v_mfma_f32_16x16x32_bf16 v[44:47], v[222:225], v[180:183], v[44:47]
	v_mfma_f32_16x16x32_bf16 v[44:47], v[226:229], v[186:189], v[44:47]
	v_mfma_f32_16x16x32_bf16 v[36:39], v[214:217], v[190:193], v[36:39]
	v_mfma_f32_16x16x32_bf16 v[36:39], v[218:221], v[194:197], v[36:39]
	v_mfma_f32_16x16x32_bf16 v[28:31], v[222:225], v[190:193], v[28:31]
	v_mfma_f32_16x16x32_bf16 v[28:31], v[226:229], v[194:197], v[28:31]
	v_mfma_f32_16x16x32_bf16 v[20:23], v[214:217], v[198:201], v[20:23]
	v_mfma_f32_16x16x32_bf16 v[20:23], v[218:221], v[202:205], v[20:23]
	v_mfma_f32_16x16x32_bf16 v[12:15], v[222:225], v[198:201], v[12:15]
	v_mfma_f32_16x16x32_bf16 v[12:15], v[226:229], v[202:205], v[12:15]
	v_mfma_f32_16x16x32_bf16 v[4:7], v[214:217], v[206:209], v[4:7]
	v_mfma_f32_16x16x32_bf16 v[4:7], v[218:221], v[210:213], v[4:7]
	v_mfma_f32_16x16x32_bf16 v[0:3], v[222:225], v[206:209], v[0:3]
	v_mfma_f32_16x16x32_bf16 v[0:3], v[226:229], v[210:213], v[0:3]
	s_add_i32 s83, s83, 2
	s_add_u32 s63, s63, 0x100
	s_addc_u32 s82, s82, 0
	s_cmp_gt_u32 s83, 13
	s_mov_b64 s[42:43], s[44:45]
	s_barrier
	s_cbranch_scc0 .LBB0_301
	v_lshl_or_b32 v162, s81, 8, v141
	v_lshl_add_u32 v157, s80, 8, v137
	v_ashrrev_i32_e32 v163, 31, v162
	v_mov_b64_e32 v[160:161], s[12:13]
	v_mad_i64_i32 v[164:165], s[42:43], v157, s78, v[160:161]
	v_lshlrev_b64 v[162:163], 1, v[162:163]
	v_lshl_add_u64 v[164:165], v[164:165], 0, v[162:163]
	s_waitcnt vmcnt(6)
	v_pk_mul_f32 v[126:127], v[158:159], v[126:127] op_sel_hi:[0,1]
	v_pk_mul_f32 v[124:125], v[158:159], v[124:125] op_sel_hi:[0,1]
	v_pk_mul_f32 v[166:167], v[158:159], v[122:123] op_sel_hi:[0,1]
	v_pk_mul_f32 v[122:123], v[158:159], v[120:121] op_sel_hi:[0,1]
	v_cvt_pk_bf16_f32 v120, v124, v125
	v_cvt_pk_bf16_f32 v121, v126, v127
	v_cvt_pk_bf16_f32 v122, v122, v123
	v_cvt_pk_bf16_f32 v123, v166, v167
	global_store_dwordx4 v[164:165], v[120:123], off
	v_pk_mul_f32 v[116:117], v[158:159], v[116:117] op_sel_hi:[0,1]
	v_pk_mul_f32 v[118:119], v[158:159], v[118:119] op_sel_hi:[0,1]
	v_pk_mul_f32 v[120:121], v[158:159], v[110:111] op_sel_hi:[0,1]
	v_pk_mul_f32 v[110:111], v[158:159], v[108:109] op_sel_hi:[0,1]
	v_cvt_pk_bf16_f32 v108, v116, v117
	v_cvt_pk_bf16_f32 v109, v118, v119
	v_cvt_pk_bf16_f32 v110, v110, v111
	v_cvt_pk_bf16_f32 v111, v120, v121
	global_store_dwordx4 v[164:165], v[108:111], off offset:256
	v_pk_mul_f32 v[112:113], v[156:157], v[112:113] op_sel_hi:[0,1]
	v_pk_mul_f32 v[100:101], v[156:157], v[100:101] op_sel_hi:[0,1]
	v_or_b32_e32 v108, 16, v157
	v_mad_i64_i32 v[108:109], s[42:43], v108, s78, v[160:161]
	v_lshl_add_u64 v[108:109], v[108:109], 0, v[162:163]
	v_pk_mul_f32 v[110:111], v[156:157], v[114:115] op_sel_hi:[0,1]
	v_pk_mul_f32 v[114:115], v[156:157], v[106:107] op_sel_hi:[0,1]
	v_pk_mul_f32 v[106:107], v[156:157], v[104:105] op_sel_hi:[0,1]
	v_cvt_pk_bf16_f32 v104, v112, v113
	v_cvt_pk_bf16_f32 v105, v110, v111
	v_cvt_pk_bf16_f32 v106, v106, v107
	v_cvt_pk_bf16_f32 v107, v114, v115
	global_store_dwordx4 v[108:109], v[104:107], off
	v_pk_mul_f32 v[102:103], v[156:157], v[102:103] op_sel_hi:[0,1]
	v_pk_mul_f32 v[96:97], v[154:155], v[96:97] op_sel_hi:[0,1]
	v_pk_mul_f32 v[104:105], v[156:157], v[94:95] op_sel_hi:[0,1]
	v_pk_mul_f32 v[94:95], v[156:157], v[92:93] op_sel_hi:[0,1]
	v_cvt_pk_bf16_f32 v92, v100, v101
	v_cvt_pk_bf16_f32 v93, v102, v103
	v_cvt_pk_bf16_f32 v94, v94, v95
	v_cvt_pk_bf16_f32 v95, v104, v105
	global_store_dwordx4 v[108:109], v[92:95], off offset:256
	v_pk_mul_f32 v[84:85], v[154:155], v[84:85] op_sel_hi:[0,1]
	v_pk_mul_f32 v[86:87], v[154:155], v[86:87] op_sel_hi:[0,1]
	v_or_b32_e32 v92, 32, v157
	v_mad_i64_i32 v[92:93], s[42:43], v92, s78, v[160:161]
	v_lshl_add_u64 v[92:93], v[92:93], 0, v[162:163]
	v_pk_mul_f32 v[94:95], v[154:155], v[98:99] op_sel_hi:[0,1]
	v_pk_mul_f32 v[98:99], v[154:155], v[90:91] op_sel_hi:[0,1]
	v_pk_mul_f32 v[90:91], v[154:155], v[88:89] op_sel_hi:[0,1]
	v_cvt_pk_bf16_f32 v88, v96, v97
	v_cvt_pk_bf16_f32 v89, v94, v95
	v_cvt_pk_bf16_f32 v90, v90, v91
	v_cvt_pk_bf16_f32 v91, v98, v99
	global_store_dwordx4 v[92:93], v[88:91], off
	v_pk_mul_f32 v[80:81], v[152:153], v[80:81] op_sel_hi:[0,1]
	v_pk_mul_f32 v[68:69], v[152:153], v[68:69] op_sel_hi:[0,1]
	v_pk_mul_f32 v[88:89], v[154:155], v[78:79] op_sel_hi:[0,1]
	v_pk_mul_f32 v[78:79], v[154:155], v[76:77] op_sel_hi:[0,1]
	v_cvt_pk_bf16_f32 v76, v84, v85
	v_cvt_pk_bf16_f32 v77, v86, v87
	v_cvt_pk_bf16_f32 v78, v78, v79
	v_cvt_pk_bf16_f32 v79, v88, v89
	global_store_dwordx4 v[92:93], v[76:79], off offset:256
	v_pk_mul_f32 v[70:71], v[152:153], v[70:71] op_sel_hi:[0,1]
	v_pk_mul_f32 v[62:63], v[150:151], v[62:63] op_sel_hi:[0,1]
	v_or_b32_e32 v76, 48, v157
	v_mad_i64_i32 v[76:77], s[42:43], v76, s78, v[160:161]
	v_lshl_add_u64 v[76:77], v[76:77], 0, v[162:163]
	v_pk_mul_f32 v[78:79], v[152:153], v[82:83] op_sel_hi:[0,1]
	v_pk_mul_f32 v[82:83], v[152:153], v[74:75] op_sel_hi:[0,1]
	v_pk_mul_f32 v[74:75], v[152:153], v[72:73] op_sel_hi:[0,1]
	v_cvt_pk_bf16_f32 v72, v80, v81
	v_cvt_pk_bf16_f32 v73, v78, v79
	v_cvt_pk_bf16_f32 v74, v74, v75
	v_cvt_pk_bf16_f32 v75, v82, v83
	global_store_dwordx4 v[76:77], v[72:75], off
	v_pk_mul_f32 v[60:61], v[150:151], v[60:61] op_sel_hi:[0,1]
	v_pk_mul_f32 v[52:53], v[150:151], v[52:53] op_sel_hi:[0,1]
	v_pk_mul_f32 v[72:73], v[152:153], v[66:67] op_sel_hi:[0,1]
	v_pk_mul_f32 v[66:67], v[152:153], v[64:65] op_sel_hi:[0,1]
	v_cvt_pk_bf16_f32 v64, v68, v69
	v_cvt_pk_bf16_f32 v65, v70, v71
	v_cvt_pk_bf16_f32 v66, v66, v67
	v_cvt_pk_bf16_f32 v67, v72, v73
	global_store_dwordx4 v[76:77], v[64:67], off offset:256
	v_pk_mul_f32 v[54:55], v[150:151], v[54:55] op_sel_hi:[0,1]
	v_pk_mul_f32 v[48:49], v[140:141], v[48:49] op_sel_hi:[0,1]
	v_add_u32_e32 v64, 0x80, v157
	v_mad_i64_i32 v[64:65], s[42:43], v64, s78, v[160:161]
	v_lshl_add_u64 v[64:65], v[64:65], 0, v[162:163]
	v_pk_mul_f32 v[66:67], v[150:151], v[58:59] op_sel_hi:[0,1]
	v_pk_mul_f32 v[58:59], v[150:151], v[56:57] op_sel_hi:[0,1]
	v_cvt_pk_bf16_f32 v56, v60, v61
	v_cvt_pk_bf16_f32 v57, v62, v63
	v_cvt_pk_bf16_f32 v58, v58, v59
	v_cvt_pk_bf16_f32 v59, v66, v67
	global_store_dwordx4 v[64:65], v[56:59], off
	v_pk_mul_f32 v[36:37], v[140:141], v[36:37] op_sel_hi:[0,1]
	v_pk_mul_f32 v[38:39], v[140:141], v[38:39] op_sel_hi:[0,1]
	v_pk_mul_f32 v[56:57], v[150:151], v[46:47] op_sel_hi:[0,1]
	v_pk_mul_f32 v[46:47], v[150:151], v[44:45] op_sel_hi:[0,1]
	v_cvt_pk_bf16_f32 v44, v52, v53
	v_cvt_pk_bf16_f32 v45, v54, v55
	v_cvt_pk_bf16_f32 v46, v46, v47
	v_cvt_pk_bf16_f32 v47, v56, v57
	global_store_dwordx4 v[64:65], v[44:47], off offset:256
	v_pk_mul_f32 v[32:33], v[138:139], v[32:33] op_sel_hi:[0,1]
	v_pk_mul_f32 v[20:21], v[138:139], v[20:21] op_sel_hi:[0,1]
	v_add_u32_e32 v44, 0x90, v157
	v_mad_i64_i32 v[44:45], s[42:43], v44, s78, v[160:161]
	v_lshl_add_u64 v[44:45], v[44:45], 0, v[162:163]
	v_pk_mul_f32 v[46:47], v[140:141], v[50:51] op_sel_hi:[0,1]
	v_pk_mul_f32 v[50:51], v[140:141], v[42:43] op_sel_hi:[0,1]
	v_pk_mul_f32 v[42:43], v[140:141], v[40:41] op_sel_hi:[0,1]
	v_cvt_pk_bf16_f32 v40, v48, v49
	v_cvt_pk_bf16_f32 v41, v46, v47
	v_cvt_pk_bf16_f32 v42, v42, v43
	v_cvt_pk_bf16_f32 v43, v50, v51
	global_store_dwordx4 v[44:45], v[40:43], off
	v_pk_mul_f32 v[22:23], v[138:139], v[22:23] op_sel_hi:[0,1]
	v_pk_mul_f32 v[16:17], v[136:137], v[16:17] op_sel_hi:[0,1]
	v_pk_mul_f32 v[40:41], v[140:141], v[30:31] op_sel_hi:[0,1]
	v_pk_mul_f32 v[30:31], v[140:141], v[28:29] op_sel_hi:[0,1]
	v_cvt_pk_bf16_f32 v28, v36, v37
	v_cvt_pk_bf16_f32 v29, v38, v39
	v_cvt_pk_bf16_f32 v30, v30, v31
	v_cvt_pk_bf16_f32 v31, v40, v41
	global_store_dwordx4 v[44:45], v[28:31], off offset:256
	s_and_b64 vcc, s[8:9], exec
	v_pk_mul_f32 v[6:7], v[136:137], v[6:7] op_sel_hi:[0,1]
	v_add_u32_e32 v28, 0xa0, v157
	v_mad_i64_i32 v[28:29], s[42:43], v28, s78, v[160:161]
	v_lshl_add_u64 v[28:29], v[28:29], 0, v[162:163]
	v_pk_mul_f32 v[30:31], v[138:139], v[34:35] op_sel_hi:[0,1]
	v_pk_mul_f32 v[34:35], v[138:139], v[26:27] op_sel_hi:[0,1]
	v_pk_mul_f32 v[26:27], v[138:139], v[24:25] op_sel_hi:[0,1]
	v_cvt_pk_bf16_f32 v24, v32, v33
	v_cvt_pk_bf16_f32 v25, v30, v31
	v_cvt_pk_bf16_f32 v26, v26, v27
	v_cvt_pk_bf16_f32 v27, v34, v35
	global_store_dwordx4 v[28:29], v[24:27], off
	v_pk_mul_f32 v[4:5], v[136:137], v[4:5] op_sel_hi:[0,1]
	s_nop 0
	v_pk_mul_f32 v[24:25], v[138:139], v[14:15] op_sel_hi:[0,1]
	v_pk_mul_f32 v[14:15], v[138:139], v[12:13] op_sel_hi:[0,1]
	v_cvt_pk_bf16_f32 v12, v20, v21
	v_cvt_pk_bf16_f32 v13, v22, v23
	v_cvt_pk_bf16_f32 v14, v14, v15
	v_cvt_pk_bf16_f32 v15, v24, v25
	global_store_dwordx4 v[28:29], v[12:15], off offset:256
	s_nop 1
	v_add_u32_e32 v12, 0xb0, v157
	v_mad_i64_i32 v[12:13], s[42:43], v12, s78, v[160:161]
	v_lshl_add_u64 v[12:13], v[12:13], 0, v[162:163]
	v_pk_mul_f32 v[14:15], v[136:137], v[18:19] op_sel_hi:[0,1]
	v_pk_mul_f32 v[18:19], v[136:137], v[10:11] op_sel_hi:[0,1]
	v_pk_mul_f32 v[10:11], v[136:137], v[8:9] op_sel_hi:[0,1]
	v_cvt_pk_bf16_f32 v8, v16, v17
	v_cvt_pk_bf16_f32 v9, v14, v15
	v_cvt_pk_bf16_f32 v10, v10, v11
	v_cvt_pk_bf16_f32 v11, v18, v19
	global_store_dwordx4 v[12:13], v[8:11], off
	s_mov_b64 s[42:43], -1
	s_nop 0
	v_pk_mul_f32 v[8:9], v[136:137], v[2:3] op_sel_hi:[0,1]
	v_pk_mul_f32 v[2:3], v[136:137], v[0:1] op_sel_hi:[0,1]
	v_cvt_pk_bf16_f32 v0, v4, v5
	v_cvt_pk_bf16_f32 v1, v6, v7
	v_cvt_pk_bf16_f32 v2, v2, v3
	v_cvt_pk_bf16_f32 v3, v8, v9
	global_store_dwordx4 v[12:13], v[0:3], off offset:256
	s_cbranch_vccz .LBB0_295
	s_nop 0
	v_lshl_add_u32 v0, s79, 8, v137
	v_ashrrev_i32_e32 v1, 31, v0
	v_lshl_add_u64 v[0:1], v[0:1], 2, s[72:73]
	global_load_dword v158, v[0:1], off
	global_load_dword v156, v[0:1], off offset:64
	global_load_dword v154, v[0:1], off offset:128
	global_load_dword v152, v[0:1], off offset:192
	global_load_dword v150, v[0:1], off offset:512
	global_load_dword v140, v[0:1], off offset:576
	global_load_dword v138, v[0:1], off offset:640
	global_load_dword v136, v[0:1], off offset:704
	s_mov_b64 s[42:43], 0
	s_branch .LBB0_295

.LBB0_325:
	ds_read_b128 v[160:163], v151
	ds_read_b128 v[164:167], v151 offset:1024
	ds_read_b128 v[168:171], v151 offset:2048
	ds_read_b128 v[176:179], v151 offset:3072
	s_add_u32 s48, s46, 0x100
	s_addc_u32 s49, s47, 0
	s_cmp_eq_u32 s91, 4
	s_cselect_b32 s53, s43, s49
	s_cselect_b32 s52, s42, s48
	s_cselect_b32 s51, s41, s90
	s_cselect_b32 s50, s62, s63
	v_lshl_add_u64 v[214:215], s[46:47], 0, v[142:143]
	s_add_i32 m0, s55, 0xc000
	ds_read_b128 v[180:183], v153
	ds_read_b128 v[186:189], v153 offset:1024
	ds_read_b128 v[190:193], v153 offset:2048
	ds_read_b128 v[194:197], v153 offset:3072
	ds_read_b128 v[198:201], v153 offset:4096
	ds_read_b128 v[202:205], v153 offset:5120
	ds_read_b128 v[206:209], v153 offset:6144
	ds_read_b128 v[210:213], v153 offset:7168
	global_load_lds_dwordx4 v[214:215], off
	v_lshl_add_u64 v[214:215], s[46:47], 0, v[144:145]
	s_add_i32 m0, s55, 0xe000
	s_nop 0
	global_load_lds_dwordx4 v[214:215], off
	s_waitcnt lgkmcnt(8)
	s_barrier
	s_waitcnt lgkmcnt(0)
	s_waitcnt lgkmcnt(0)
	v_mfma_f32_16x16x32_bf16 v[124:127], v[160:163], v[180:183], v[124:127]
	v_mfma_f32_16x16x32_bf16 v[124:127], v[164:167], v[186:189], v[124:127]
	v_mfma_f32_16x16x32_bf16 v[120:123], v[168:171], v[180:183], v[120:123]
	v_mfma_f32_16x16x32_bf16 v[120:123], v[176:179], v[186:189], v[120:123]
	v_mfma_f32_16x16x32_bf16 v[108:111], v[160:163], v[190:193], v[108:111]
	v_mfma_f32_16x16x32_bf16 v[108:111], v[164:167], v[194:197], v[108:111]
	v_mfma_f32_16x16x32_bf16 v[104:107], v[168:171], v[190:193], v[104:107]
	v_mfma_f32_16x16x32_bf16 v[104:107], v[176:179], v[194:197], v[104:107]
	v_mfma_f32_16x16x32_bf16 v[92:95], v[160:163], v[198:201], v[92:95]
	v_mfma_f32_16x16x32_bf16 v[92:95], v[164:167], v[202:205], v[92:95]
	v_mfma_f32_16x16x32_bf16 v[88:91], v[168:171], v[198:201], v[88:91]
	v_mfma_f32_16x16x32_bf16 v[88:91], v[176:179], v[202:205], v[88:91]
	v_mfma_f32_16x16x32_bf16 v[76:79], v[160:163], v[206:209], v[76:79]
	v_mfma_f32_16x16x32_bf16 v[76:79], v[164:167], v[210:213], v[76:79]
	v_mfma_f32_16x16x32_bf16 v[72:75], v[168:171], v[206:209], v[72:75]
	v_mfma_f32_16x16x32_bf16 v[72:75], v[176:179], v[210:213], v[72:75]
	s_barrier
	s_add_i32 s46, s81, s54
	v_lshl_add_u64 v[230:231], s[50:51], 0, v[130:131]
	s_mov_b32 m0, s46
	ds_read_b128 v[214:217], v155
	ds_read_b128 v[218:221], v155 offset:1024
	ds_read_b128 v[222:225], v155 offset:2048
	ds_read_b128 v[226:229], v155 offset:3072
	global_load_lds_dwordx4 v[230:231], off
	v_lshl_add_u64 v[232:233], s[50:51], 0, v[134:135]
	s_add_i32 m0, s46, 0x2000
	s_nop 0
	global_load_lds_dwordx4 v[232:233], off
	s_barrier
	s_waitcnt lgkmcnt(0)
	s_waitcnt lgkmcnt(0)
	v_mfma_f32_16x16x32_bf16 v[116:119], v[214:217], v[180:183], v[116:119]
	v_mfma_f32_16x16x32_bf16 v[116:119], v[218:221], v[186:189], v[116:119]
	v_mfma_f32_16x16x32_bf16 v[112:115], v[222:225], v[180:183], v[112:115]
	v_mfma_f32_16x16x32_bf16 v[112:115], v[226:229], v[186:189], v[112:115]
	v_mfma_f32_16x16x32_bf16 v[100:103], v[214:217], v[190:193], v[100:103]
	v_mfma_f32_16x16x32_bf16 v[100:103], v[218:221], v[194:197], v[100:103]
	v_mfma_f32_16x16x32_bf16 v[96:99], v[222:225], v[190:193], v[96:99]
	v_mfma_f32_16x16x32_bf16 v[96:99], v[226:229], v[194:197], v[96:99]
	v_mfma_f32_16x16x32_bf16 v[84:87], v[214:217], v[198:201], v[84:87]
	v_mfma_f32_16x16x32_bf16 v[84:87], v[218:221], v[202:205], v[84:87]
	v_mfma_f32_16x16x32_bf16 v[80:83], v[222:225], v[198:201], v[80:83]
	v_mfma_f32_16x16x32_bf16 v[80:83], v[226:229], v[202:205], v[80:83]
	v_mfma_f32_16x16x32_bf16 v[68:71], v[214:217], v[206:209], v[68:71]
	v_mfma_f32_16x16x32_bf16 v[68:71], v[218:221], v[210:213], v[68:71]
	v_mfma_f32_16x16x32_bf16 v[64:67], v[222:225], v[206:209], v[64:67]
	v_mfma_f32_16x16x32_bf16 v[64:67], v[226:229], v[210:213], v[64:67]
	s_mov_b32 m0, s55
	v_lshl_add_u64 v[234:235], s[52:53], 0, v[128:129]
	s_barrier
	ds_read_b128 v[180:183], v153 offset:16384
	ds_read_b128 v[186:189], v153 offset:17408
	ds_read_b128 v[190:193], v153 offset:18432
	ds_read_b128 v[194:197], v153 offset:19456
	ds_read_b128 v[198:201], v153 offset:20480
	ds_read_b128 v[202:205], v153 offset:21504
	ds_read_b128 v[206:209], v153 offset:22528
	ds_read_b128 v[210:213], v153 offset:23552
	global_load_lds_dwordx4 v[234:235], off
	v_lshl_add_u64 v[236:237], s[52:53], 0, v[132:133]
	s_mov_b32 m0, s61
	s_nop 0
	global_load_lds_dwordx4 v[236:237], off
	s_barrier
	s_waitcnt lgkmcnt(0)
	s_waitcnt lgkmcnt(0)
	v_mfma_f32_16x16x32_bf16 v[60:63], v[160:163], v[180:183], v[60:63]
	v_mfma_f32_16x16x32_bf16 v[60:63], v[164:167], v[186:189], v[60:63]
	v_mfma_f32_16x16x32_bf16 v[56:59], v[168:171], v[180:183], v[56:59]
	v_mfma_f32_16x16x32_bf16 v[56:59], v[176:179], v[186:189], v[56:59]
	v_mfma_f32_16x16x32_bf16 v[48:51], v[160:163], v[190:193], v[48:51]
	v_mfma_f32_16x16x32_bf16 v[48:51], v[164:167], v[194:197], v[48:51]
	v_mfma_f32_16x16x32_bf16 v[40:43], v[168:171], v[190:193], v[40:43]
	v_mfma_f32_16x16x32_bf16 v[40:43], v[176:179], v[194:197], v[40:43]
	v_mfma_f32_16x16x32_bf16 v[32:35], v[160:163], v[198:201], v[32:35]
	v_mfma_f32_16x16x32_bf16 v[32:35], v[164:167], v[202:205], v[32:35]
	v_mfma_f32_16x16x32_bf16 v[24:27], v[168:171], v[198:201], v[24:27]
	v_mfma_f32_16x16x32_bf16 v[24:27], v[176:179], v[202:205], v[24:27]
	v_mfma_f32_16x16x32_bf16 v[16:19], v[160:163], v[206:209], v[16:19]
	v_mfma_f32_16x16x32_bf16 v[16:19], v[164:167], v[210:213], v[16:19]
	v_mfma_f32_16x16x32_bf16 v[8:11], v[168:171], v[206:209], v[8:11]
	v_mfma_f32_16x16x32_bf16 v[8:11], v[176:179], v[210:213], v[8:11]
	s_barrier
	s_add_u32 s46, s50, 0x20000
	s_addc_u32 s47, s51, 0
	s_add_i32 s92, s82, s54
	v_lshl_add_u64 v[160:161], s[46:47], 0, v[130:131]
	s_mov_b32 m0, s92
	s_nop 0
	global_load_lds_dwordx4 v[160:161], off
	v_lshl_add_u64 v[160:161], s[46:47], 0, v[134:135]
	s_add_i32 m0, s92, 0x2000
	s_nop 0
	global_load_lds_dwordx4 v[160:161], off
	s_waitcnt vmcnt(6)
	s_barrier
	v_mfma_f32_16x16x32_bf16 v[52:55], v[214:217], v[180:183], v[52:55]
	v_mfma_f32_16x16x32_bf16 v[52:55], v[218:221], v[186:189], v[52:55]
	v_mfma_f32_16x16x32_bf16 v[44:47], v[222:225], v[180:183], v[44:47]
	v_mfma_f32_16x16x32_bf16 v[44:47], v[226:229], v[186:189], v[44:47]
	v_mfma_f32_16x16x32_bf16 v[36:39], v[214:217], v[190:193], v[36:39]
	v_mfma_f32_16x16x32_bf16 v[36:39], v[218:221], v[194:197], v[36:39]
	v_mfma_f32_16x16x32_bf16 v[28:31], v[222:225], v[190:193], v[28:31]
	v_mfma_f32_16x16x32_bf16 v[28:31], v[226:229], v[194:197], v[28:31]
	v_mfma_f32_16x16x32_bf16 v[20:23], v[214:217], v[198:201], v[20:23]
	v_mfma_f32_16x16x32_bf16 v[20:23], v[218:221], v[202:205], v[20:23]
	v_mfma_f32_16x16x32_bf16 v[12:15], v[222:225], v[198:201], v[12:15]
	v_mfma_f32_16x16x32_bf16 v[12:15], v[226:229], v[202:205], v[12:15]
	v_mfma_f32_16x16x32_bf16 v[4:7], v[214:217], v[206:209], v[4:7]
	v_mfma_f32_16x16x32_bf16 v[4:7], v[218:221], v[210:213], v[4:7]
	v_mfma_f32_16x16x32_bf16 v[0:3], v[222:225], v[206:209], v[0:3]
	v_mfma_f32_16x16x32_bf16 v[0:3], v[226:229], v[210:213], v[0:3]
	s_add_i32 s92, 0, 0x18000
	v_add_u32_e32 v157, s92, v139
	s_barrier
	ds_read_b128 v[160:163], v157
	ds_read_b128 v[164:167], v157 offset:1024
	ds_read_b128 v[168:171], v157 offset:2048
	ds_read_b128 v[176:179], v157 offset:3072
	s_add_u32 s46, s52, 0x170000
	s_addc_u32 s47, s53, 0
	s_mov_b32 m0, s74
	v_lshl_add_u64 v[214:215], s[46:47], 0, v[128:129]
	ds_read_b128 v[180:183], v153 offset:32768
	ds_read_b128 v[186:189], v153 offset:33792
	ds_read_b128 v[190:193], v153 offset:34816
	ds_read_b128 v[194:197], v153 offset:35840
	ds_read_b128 v[198:201], v153 offset:36864
	ds_read_b128 v[202:205], v153 offset:37888
	ds_read_b128 v[206:209], v153 offset:38912
	ds_read_b128 v[210:213], v153 offset:39936
	global_load_lds_dwordx4 v[214:215], off
	v_lshl_add_u64 v[214:215], s[46:47], 0, v[132:133]
	s_mov_b32 m0, s75
	s_nop 0
	global_load_lds_dwordx4 v[214:215], off
	s_waitcnt lgkmcnt(8)
	s_barrier
	s_waitcnt lgkmcnt(0)
	s_waitcnt lgkmcnt(0)
	v_mfma_f32_16x16x32_bf16 v[124:127], v[160:163], v[180:183], v[124:127]
	v_mfma_f32_16x16x32_bf16 v[124:127], v[164:167], v[186:189], v[124:127]
	v_mfma_f32_16x16x32_bf16 v[120:123], v[168:171], v[180:183], v[120:123]
	v_mfma_f32_16x16x32_bf16 v[120:123], v[176:179], v[186:189], v[120:123]
	v_mfma_f32_16x16x32_bf16 v[108:111], v[160:163], v[190:193], v[108:111]
	v_mfma_f32_16x16x32_bf16 v[108:111], v[164:167], v[194:197], v[108:111]
	v_mfma_f32_16x16x32_bf16 v[104:107], v[168:171], v[190:193], v[104:107]
	v_mfma_f32_16x16x32_bf16 v[104:107], v[176:179], v[194:197], v[104:107]
	v_mfma_f32_16x16x32_bf16 v[92:95], v[160:163], v[198:201], v[92:95]
	v_mfma_f32_16x16x32_bf16 v[92:95], v[164:167], v[202:205], v[92:95]
	v_mfma_f32_16x16x32_bf16 v[88:91], v[168:171], v[198:201], v[88:91]
	v_mfma_f32_16x16x32_bf16 v[88:91], v[176:179], v[202:205], v[88:91]
	v_mfma_f32_16x16x32_bf16 v[76:79], v[160:163], v[206:209], v[76:79]
	v_mfma_f32_16x16x32_bf16 v[76:79], v[164:167], v[210:213], v[76:79]
	v_mfma_f32_16x16x32_bf16 v[72:75], v[168:171], v[206:209], v[72:75]
	v_mfma_f32_16x16x32_bf16 v[72:75], v[176:179], v[210:213], v[72:75]
	s_barrier
	s_add_i32 s52, 0, 0x1c000
	s_add_i32 s46, s92, s54
	v_add_u32_e32 v157, s52, v139
	v_lshl_add_u64 v[230:231], v[230:231], 0, s[10:11]
	s_mov_b32 m0, s46
	ds_read_b128 v[214:217], v157
	ds_read_b128 v[218:221], v157 offset:1024
	ds_read_b128 v[222:225], v157 offset:2048
	ds_read_b128 v[226:229], v157 offset:3072
	global_load_lds_dwordx4 v[230:231], off
	v_lshl_add_u64 v[230:231], v[232:233], 0, s[10:11]
	s_add_i32 m0, s46, 0x2000
	s_nop 0
	global_load_lds_dwordx4 v[230:231], off
	s_barrier
	s_waitcnt lgkmcnt(0)
	s_waitcnt lgkmcnt(0)
	v_mfma_f32_16x16x32_bf16 v[116:119], v[214:217], v[180:183], v[116:119]
	v_mfma_f32_16x16x32_bf16 v[116:119], v[218:221], v[186:189], v[116:119]
	v_mfma_f32_16x16x32_bf16 v[112:115], v[222:225], v[180:183], v[112:115]
	v_mfma_f32_16x16x32_bf16 v[112:115], v[226:229], v[186:189], v[112:115]
	v_mfma_f32_16x16x32_bf16 v[100:103], v[214:217], v[190:193], v[100:103]
	v_mfma_f32_16x16x32_bf16 v[100:103], v[218:221], v[194:197], v[100:103]
	v_mfma_f32_16x16x32_bf16 v[96:99], v[222:225], v[190:193], v[96:99]
	v_mfma_f32_16x16x32_bf16 v[96:99], v[226:229], v[194:197], v[96:99]
	v_mfma_f32_16x16x32_bf16 v[84:87], v[214:217], v[198:201], v[84:87]
	v_mfma_f32_16x16x32_bf16 v[84:87], v[218:221], v[202:205], v[84:87]
	v_mfma_f32_16x16x32_bf16 v[80:83], v[222:225], v[198:201], v[80:83]
	v_mfma_f32_16x16x32_bf16 v[80:83], v[226:229], v[202:205], v[80:83]
	v_mfma_f32_16x16x32_bf16 v[68:71], v[214:217], v[206:209], v[68:71]
	v_mfma_f32_16x16x32_bf16 v[68:71], v[218:221], v[210:213], v[68:71]
	v_mfma_f32_16x16x32_bf16 v[64:67], v[222:225], v[206:209], v[64:67]
	v_mfma_f32_16x16x32_bf16 v[64:67], v[226:229], v[210:213], v[64:67]
	s_mov_b32 m0, s77
	v_lshl_add_u64 v[230:231], v[234:235], 0, s[10:11]
	s_barrier
	ds_read_b128 v[180:183], v153 offset:49152
	ds_read_b128 v[186:189], v153 offset:50176
	ds_read_b128 v[190:193], v153 offset:51200
	ds_read_b128 v[194:197], v153 offset:52224
	ds_read_b128 v[198:201], v153 offset:53248
	ds_read_b128 v[202:205], v153 offset:54272
	ds_read_b128 v[206:209], v153 offset:55296
	ds_read_b128 v[210:213], v153 offset:56320
	global_load_lds_dwordx4 v[230:231], off
	v_lshl_add_u64 v[230:231], v[236:237], 0, s[10:11]
	s_mov_b32 m0, s78
	s_nop 0
	global_load_lds_dwordx4 v[230:231], off
	s_barrier
	s_waitcnt lgkmcnt(0)
	s_waitcnt lgkmcnt(0)
	v_mfma_f32_16x16x32_bf16 v[60:63], v[160:163], v[180:183], v[60:63]
	v_mfma_f32_16x16x32_bf16 v[60:63], v[164:167], v[186:189], v[60:63]
	v_mfma_f32_16x16x32_bf16 v[56:59], v[168:171], v[180:183], v[56:59]
	v_mfma_f32_16x16x32_bf16 v[56:59], v[176:179], v[186:189], v[56:59]
	v_mfma_f32_16x16x32_bf16 v[48:51], v[160:163], v[190:193], v[48:51]
	v_mfma_f32_16x16x32_bf16 v[48:51], v[164:167], v[194:197], v[48:51]
	v_mfma_f32_16x16x32_bf16 v[40:43], v[168:171], v[190:193], v[40:43]
	v_mfma_f32_16x16x32_bf16 v[40:43], v[176:179], v[194:197], v[40:43]
	v_mfma_f32_16x16x32_bf16 v[32:35], v[160:163], v[198:201], v[32:35]
	v_mfma_f32_16x16x32_bf16 v[32:35], v[164:167], v[202:205], v[32:35]
	v_mfma_f32_16x16x32_bf16 v[24:27], v[168:171], v[198:201], v[24:27]
	v_mfma_f32_16x16x32_bf16 v[24:27], v[176:179], v[202:205], v[24:27]
	v_mfma_f32_16x16x32_bf16 v[16:19], v[160:163], v[206:209], v[16:19]
	v_mfma_f32_16x16x32_bf16 v[16:19], v[164:167], v[210:213], v[16:19]
	v_mfma_f32_16x16x32_bf16 v[8:11], v[168:171], v[206:209], v[8:11]
	v_mfma_f32_16x16x32_bf16 v[8:11], v[176:179], v[210:213], v[8:11]
	s_barrier
	s_add_u32 s46, s50, 0x20080
	s_addc_u32 s47, s51, 0
	s_add_i32 s50, s52, s54
	v_lshl_add_u64 v[160:161], s[46:47], 0, v[130:131]
	s_mov_b32 m0, s50
	s_nop 0
	global_load_lds_dwordx4 v[160:161], off
	v_lshl_add_u64 v[160:161], s[46:47], 0, v[134:135]
	s_add_i32 m0, s50, 0x2000
	s_nop 0
	global_load_lds_dwordx4 v[160:161], off
	s_waitcnt vmcnt(6)
	s_barrier
	v_mfma_f32_16x16x32_bf16 v[52:55], v[214:217], v[180:183], v[52:55]
	v_mfma_f32_16x16x32_bf16 v[52:55], v[218:221], v[186:189], v[52:55]
	v_mfma_f32_16x16x32_bf16 v[44:47], v[222:225], v[180:183], v[44:47]
	v_mfma_f32_16x16x32_bf16 v[44:47], v[226:229], v[186:189], v[44:47]
	v_mfma_f32_16x16x32_bf16 v[36:39], v[214:217], v[190:193], v[36:39]
	v_mfma_f32_16x16x32_bf16 v[36:39], v[218:221], v[194:197], v[36:39]
	v_mfma_f32_16x16x32_bf16 v[28:31], v[222:225], v[190:193], v[28:31]
	v_mfma_f32_16x16x32_bf16 v[28:31], v[226:229], v[194:197], v[28:31]
	v_mfma_f32_16x16x32_bf16 v[20:23], v[214:217], v[198:201], v[20:23]
	v_mfma_f32_16x16x32_bf16 v[20:23], v[218:221], v[202:205], v[20:23]
	v_mfma_f32_16x16x32_bf16 v[12:15], v[222:225], v[198:201], v[12:15]
	v_mfma_f32_16x16x32_bf16 v[12:15], v[226:229], v[202:205], v[12:15]
	v_mfma_f32_16x16x32_bf16 v[4:7], v[214:217], v[206:209], v[4:7]
	v_mfma_f32_16x16x32_bf16 v[4:7], v[218:221], v[210:213], v[4:7]
	v_mfma_f32_16x16x32_bf16 v[0:3], v[222:225], v[206:209], v[0:3]
	v_mfma_f32_16x16x32_bf16 v[0:3], v[226:229], v[210:213], v[0:3]
	s_add_i32 s91, s91, 2
	s_add_u32 s63, s63, 0x100
	s_addc_u32 s90, s90, 0
	s_cmp_gt_u32 s91, 5
	s_mov_b64 s[46:47], s[48:49]
	s_barrier
	s_cbranch_scc0 .LBB0_325
	v_lshl_add_u32 v162, s88, 8, v137
	v_lshl_or_b32 v160, s89, 8, v141
	v_ashrrev_i32_e32 v163, 31, v162
	v_ashrrev_i32_e32 v161, 31, v160
	v_lshlrev_b64 v[164:165], 14, v[162:163]
	v_lshl_add_u64 v[164:165], s[56:57], 0, v[164:165]
	v_lshlrev_b64 v[166:167], 1, v[160:161]
	v_lshl_add_u64 v[160:161], v[164:165], 0, v[166:167]
	s_waitcnt vmcnt(6)
	v_pk_mul_f32 v[126:127], v[158:159], v[126:127] op_sel_hi:[0,1]
	v_pk_mul_f32 v[124:125], v[158:159], v[124:125] op_sel_hi:[0,1]
	v_pk_mul_f32 v[164:165], v[158:159], v[122:123] op_sel_hi:[0,1]
	v_pk_mul_f32 v[122:123], v[158:159], v[120:121] op_sel_hi:[0,1]
	v_cvt_pk_bf16_f32 v120, v124, v125
	v_cvt_pk_bf16_f32 v121, v126, v127
	v_cvt_pk_bf16_f32 v122, v122, v123
	v_cvt_pk_bf16_f32 v123, v164, v165
	global_store_dwordx4 v[160:161], v[120:123], off
	v_pk_mul_f32 v[116:117], v[158:159], v[116:117] op_sel_hi:[0,1]
	v_pk_mul_f32 v[118:119], v[158:159], v[118:119] op_sel_hi:[0,1]
	v_pk_mul_f32 v[120:121], v[158:159], v[114:115] op_sel_hi:[0,1]
	v_pk_mul_f32 v[114:115], v[158:159], v[112:113] op_sel_hi:[0,1]
	v_cvt_pk_bf16_f32 v112, v116, v117
	v_cvt_pk_bf16_f32 v113, v118, v119
	v_cvt_pk_bf16_f32 v114, v114, v115
	v_cvt_pk_bf16_f32 v115, v120, v121
	global_store_dwordx4 v[160:161], v[112:115], off offset:256
	v_pk_mul_f32 v[110:111], v[156:157], v[110:111] op_sel_hi:[0,1]
	v_pk_mul_f32 v[108:109], v[156:157], v[108:109] op_sel_hi:[0,1]
	v_or_b32_e32 v112, 16, v162
	v_ashrrev_i32_e32 v113, 31, v112
	v_lshlrev_b64 v[112:113], 14, v[112:113]
	v_lshl_add_u64 v[112:113], s[56:57], 0, v[112:113]
	v_lshl_add_u64 v[112:113], v[112:113], 0, v[166:167]
	v_pk_mul_f32 v[114:115], v[156:157], v[106:107] op_sel_hi:[0,1]
	v_pk_mul_f32 v[106:107], v[156:157], v[104:105] op_sel_hi:[0,1]
	v_cvt_pk_bf16_f32 v104, v108, v109
	v_cvt_pk_bf16_f32 v105, v110, v111
	v_cvt_pk_bf16_f32 v106, v106, v107
	v_cvt_pk_bf16_f32 v107, v114, v115
	global_store_dwordx4 v[112:113], v[104:107], off
	v_pk_mul_f32 v[100:101], v[156:157], v[100:101] op_sel_hi:[0,1]
	v_pk_mul_f32 v[102:103], v[156:157], v[102:103] op_sel_hi:[0,1]
	v_pk_mul_f32 v[104:105], v[156:157], v[98:99] op_sel_hi:[0,1]
	v_pk_mul_f32 v[98:99], v[156:157], v[96:97] op_sel_hi:[0,1]
	v_cvt_pk_bf16_f32 v96, v100, v101
	v_cvt_pk_bf16_f32 v97, v102, v103
	v_cvt_pk_bf16_f32 v98, v98, v99
	v_cvt_pk_bf16_f32 v99, v104, v105
	global_store_dwordx4 v[112:113], v[96:99], off offset:256
	v_pk_mul_f32 v[94:95], v[154:155], v[94:95] op_sel_hi:[0,1]
	v_pk_mul_f32 v[92:93], v[154:155], v[92:93] op_sel_hi:[0,1]
	v_or_b32_e32 v96, 32, v162
	v_ashrrev_i32_e32 v97, 31, v96
	v_lshlrev_b64 v[96:97], 14, v[96:97]
	v_lshl_add_u64 v[96:97], s[56:57], 0, v[96:97]
	v_lshl_add_u64 v[96:97], v[96:97], 0, v[166:167]
	v_pk_mul_f32 v[98:99], v[154:155], v[90:91] op_sel_hi:[0,1]
	v_pk_mul_f32 v[90:91], v[154:155], v[88:89] op_sel_hi:[0,1]
	v_cvt_pk_bf16_f32 v88, v92, v93
	v_cvt_pk_bf16_f32 v89, v94, v95
	v_cvt_pk_bf16_f32 v90, v90, v91
	v_cvt_pk_bf16_f32 v91, v98, v99
	global_store_dwordx4 v[96:97], v[88:91], off
	v_pk_mul_f32 v[84:85], v[154:155], v[84:85] op_sel_hi:[0,1]
	v_pk_mul_f32 v[86:87], v[154:155], v[86:87] op_sel_hi:[0,1]
	v_pk_mul_f32 v[88:89], v[154:155], v[82:83] op_sel_hi:[0,1]
	v_pk_mul_f32 v[82:83], v[154:155], v[80:81] op_sel_hi:[0,1]
	v_cvt_pk_bf16_f32 v80, v84, v85
	v_cvt_pk_bf16_f32 v81, v86, v87
	v_cvt_pk_bf16_f32 v82, v82, v83
	v_cvt_pk_bf16_f32 v83, v88, v89
	global_store_dwordx4 v[96:97], v[80:83], off offset:256
	v_pk_mul_f32 v[78:79], v[152:153], v[78:79] op_sel_hi:[0,1]
	v_pk_mul_f32 v[76:77], v[152:153], v[76:77] op_sel_hi:[0,1]
	v_or_b32_e32 v80, 48, v162
	v_ashrrev_i32_e32 v81, 31, v80
	v_lshlrev_b64 v[80:81], 14, v[80:81]
	v_lshl_add_u64 v[80:81], s[56:57], 0, v[80:81]
	v_lshl_add_u64 v[80:81], v[80:81], 0, v[166:167]
	v_pk_mul_f32 v[82:83], v[152:153], v[74:75] op_sel_hi:[0,1]
	v_pk_mul_f32 v[74:75], v[152:153], v[72:73] op_sel_hi:[0,1]
	v_cvt_pk_bf16_f32 v72, v76, v77
	v_cvt_pk_bf16_f32 v73, v78, v79
	v_cvt_pk_bf16_f32 v74, v74, v75
	v_cvt_pk_bf16_f32 v75, v82, v83
	global_store_dwordx4 v[80:81], v[72:75], off
	v_pk_mul_f32 v[70:71], v[152:153], v[70:71] op_sel_hi:[0,1]
	v_pk_mul_f32 v[68:69], v[152:153], v[68:69] op_sel_hi:[0,1]
	v_pk_mul_f32 v[72:73], v[152:153], v[66:67] op_sel_hi:[0,1]
	v_pk_mul_f32 v[66:67], v[152:153], v[64:65] op_sel_hi:[0,1]
	v_cvt_pk_bf16_f32 v64, v68, v69
	v_cvt_pk_bf16_f32 v65, v70, v71
	v_cvt_pk_bf16_f32 v66, v66, v67
	v_cvt_pk_bf16_f32 v67, v72, v73
	v_pk_mul_f32 v[60:61], v[150:151], v[60:61] op_sel_hi:[0,1]
	global_store_dwordx4 v[80:81], v[64:67], off offset:256
	v_pk_mul_f32 v[62:63], v[150:151], v[62:63] op_sel_hi:[0,1]
	s_mov_b64 s[46:47], 0x200000
	v_pk_mul_f32 v[66:67], v[150:151], v[58:59] op_sel_hi:[0,1]
	v_pk_mul_f32 v[58:59], v[150:151], v[56:57] op_sel_hi:[0,1]
	v_cvt_pk_bf16_f32 v56, v60, v61
	v_add_co_u32_e32 v60, vcc, s83, v160
	v_cvt_pk_bf16_f32 v57, v62, v63
	v_cvt_pk_bf16_f32 v58, v58, v59
	v_cvt_pk_bf16_f32 v59, v66, v67
	v_lshl_add_u64 v[64:65], v[160:161], 0, s[46:47]
	s_nop 0
	v_addc_co_u32_e32 v61, vcc, 0, v161, vcc
	global_store_dwordx4 v[60:61], v[56:59], off
	v_pk_mul_f32 v[54:55], v[150:151], v[54:55] op_sel_hi:[0,1]
	v_pk_mul_f32 v[52:53], v[150:151], v[52:53] op_sel_hi:[0,1]
	v_pk_mul_f32 v[56:57], v[150:151], v[46:47] op_sel_hi:[0,1]
	v_pk_mul_f32 v[46:47], v[150:151], v[44:45] op_sel_hi:[0,1]
	v_cvt_pk_bf16_f32 v44, v52, v53
	v_cvt_pk_bf16_f32 v45, v54, v55
	v_cvt_pk_bf16_f32 v46, v46, v47
	v_cvt_pk_bf16_f32 v47, v56, v57
	global_store_dwordx4 v[64:65], v[44:47], off offset:256
	v_pk_mul_f32 v[48:49], v[140:141], v[48:49] op_sel_hi:[0,1]
	v_pk_mul_f32 v[38:39], v[140:141], v[38:39] op_sel_hi:[0,1]
	v_pk_mul_f32 v[46:47], v[140:141], v[50:51] op_sel_hi:[0,1]
	v_pk_mul_f32 v[50:51], v[140:141], v[42:43] op_sel_hi:[0,1]
	v_pk_mul_f32 v[42:43], v[140:141], v[40:41] op_sel_hi:[0,1]
	v_cvt_pk_bf16_f32 v40, v48, v49
	v_cvt_pk_bf16_f32 v41, v46, v47
	v_add_co_u32_e32 v46, vcc, s84, v160
	v_cvt_pk_bf16_f32 v42, v42, v43
	v_cvt_pk_bf16_f32 v43, v50, v51
	v_lshl_add_u64 v[44:45], v[160:161], 0, s[30:31]
	s_nop 0
	v_addc_co_u32_e32 v47, vcc, 0, v161, vcc
	global_store_dwordx4 v[46:47], v[40:43], off
	v_pk_mul_f32 v[36:37], v[140:141], v[36:37] op_sel_hi:[0,1]
	v_pk_mul_f32 v[32:33], v[138:139], v[32:33] op_sel_hi:[0,1]
	v_pk_mul_f32 v[40:41], v[140:141], v[30:31] op_sel_hi:[0,1]
	v_pk_mul_f32 v[30:31], v[140:141], v[28:29] op_sel_hi:[0,1]
	v_cvt_pk_bf16_f32 v28, v36, v37
	v_cvt_pk_bf16_f32 v29, v38, v39
	v_cvt_pk_bf16_f32 v30, v30, v31
	v_cvt_pk_bf16_f32 v31, v40, v41
	global_store_dwordx4 v[44:45], v[28:31], off offset:256
	v_pk_mul_f32 v[22:23], v[138:139], v[22:23] op_sel_hi:[0,1]
	v_pk_mul_f32 v[20:21], v[138:139], v[20:21] op_sel_hi:[0,1]
	v_pk_mul_f32 v[30:31], v[138:139], v[34:35] op_sel_hi:[0,1]
	v_pk_mul_f32 v[34:35], v[138:139], v[26:27] op_sel_hi:[0,1]
	v_pk_mul_f32 v[26:27], v[138:139], v[24:25] op_sel_hi:[0,1]
	v_cvt_pk_bf16_f32 v24, v32, v33
	v_cvt_pk_bf16_f32 v25, v30, v31
	v_add_co_u32_e32 v30, vcc, s85, v160
	v_cvt_pk_bf16_f32 v26, v26, v27
	v_cvt_pk_bf16_f32 v27, v34, v35
	v_lshl_add_u64 v[28:29], v[160:161], 0, s[36:37]
	s_nop 0
	v_addc_co_u32_e32 v31, vcc, 0, v161, vcc
	global_store_dwordx4 v[30:31], v[24:27], off
	v_pk_mul_f32 v[16:17], v[136:137], v[16:17] op_sel_hi:[0,1]
	s_mov_b64 s[46:47], -1
	v_pk_mul_f32 v[24:25], v[138:139], v[14:15] op_sel_hi:[0,1]
	v_pk_mul_f32 v[14:15], v[138:139], v[12:13] op_sel_hi:[0,1]
	v_cvt_pk_bf16_f32 v12, v20, v21
	v_cvt_pk_bf16_f32 v13, v22, v23
	v_cvt_pk_bf16_f32 v14, v14, v15
	v_cvt_pk_bf16_f32 v15, v24, v25
	global_store_dwordx4 v[28:29], v[12:15], off offset:256
	v_pk_mul_f32 v[6:7], v[136:137], v[6:7] op_sel_hi:[0,1]
	v_pk_mul_f32 v[4:5], v[136:137], v[4:5] op_sel_hi:[0,1]
	v_pk_mul_f32 v[14:15], v[136:137], v[18:19] op_sel_hi:[0,1]
	v_pk_mul_f32 v[18:19], v[136:137], v[10:11] op_sel_hi:[0,1]
	v_pk_mul_f32 v[10:11], v[136:137], v[8:9] op_sel_hi:[0,1]
	v_cvt_pk_bf16_f32 v8, v16, v17
	v_cvt_pk_bf16_f32 v9, v14, v15
	v_add_co_u32_e32 v14, vcc, s86, v160
	v_lshl_add_u64 v[12:13], v[160:161], 0, s[38:39]
	s_nop 0
	v_addc_co_u32_e32 v15, vcc, 0, v161, vcc
	v_cvt_pk_bf16_f32 v10, v10, v11
	v_cvt_pk_bf16_f32 v11, v18, v19
	global_store_dwordx4 v[14:15], v[8:11], off
	s_and_b64 vcc, s[8:9], exec
	s_nop 0
	v_pk_mul_f32 v[8:9], v[136:137], v[2:3] op_sel_hi:[0,1]
	v_pk_mul_f32 v[2:3], v[136:137], v[0:1] op_sel_hi:[0,1]
	v_cvt_pk_bf16_f32 v0, v4, v5
	v_cvt_pk_bf16_f32 v1, v6, v7
	v_cvt_pk_bf16_f32 v2, v2, v3
	v_cvt_pk_bf16_f32 v3, v8, v9
	global_store_dwordx4 v[12:13], v[0:3], off offset:256
	s_cbranch_vccz .LBB0_315
	s_nop 0
	v_lshl_add_u32 v0, s87, 8, v137
	v_ashrrev_i32_e32 v1, 31, v0
	v_lshl_add_u64 v[0:1], v[0:1], 2, s[34:35]
	global_load_dword v158, v[0:1], off
	global_load_dword v156, v[0:1], off offset:64
	global_load_dword v154, v[0:1], off offset:128
	global_load_dword v152, v[0:1], off offset:192
	global_load_dword v150, v[0:1], off offset:512
	global_load_dword v140, v[0:1], off offset:576
	global_load_dword v138, v[0:1], off offset:640
	global_load_dword v136, v[0:1], off offset:704
	s_mov_b64 s[46:47], 0
	s_branch .LBB0_315
